# attention QK^T (3 in-loop blocks): K-fragment ds_read for the next step issued right after the MFMA that frees its register (one MFMA of cover instead of none)
# speedup vs baseline: 1.0095x; 1.0039x over previous
.LBB0_527:
	ds_read_b128 v[64:67], v208 offset:49152
	ds_read_b128 v[68:71], v208 offset:57344
	v_readlane_b32 s20, v255, 63
	s_cmpk_lt_i32 s20, 0x140
	s_movk_i32 s21, 0x1fff
	s_waitcnt lgkmcnt(1)
	v_mfma_f32_32x32x16_bf16 v[80:95], v[64:67], v[120:123], 0
	v_mov_b32_e32 v198, 0xbf1f24be
	s_waitcnt lgkmcnt(0)
	v_mfma_f32_32x32x16_bf16 v[64:79], v[68:71], v[120:123], 0
	ds_read_b128 v[120:123], v213 offset:49152
	s_waitcnt vmcnt(3)
	ds_read_b128 v[144:147], v213 offset:57344
	s_waitcnt lgkmcnt(1)
	v_mfma_f32_32x32x16_bf16 v[80:95], v[120:123], v[112:115], v[80:95]
	s_waitcnt lgkmcnt(0)
	v_mfma_f32_32x32x16_bf16 v[64:79], v[144:147], v[112:115], v[64:79]
	ds_read_b128 v[112:115], v214 offset:49152
	ds_read_b128 v[120:123], v214 offset:57344
	s_waitcnt lgkmcnt(1)
	v_mfma_f32_32x32x16_bf16 v[80:95], v[112:115], v[132:135], v[80:95]
	ds_read_b128 v[112:115], v215 offset:49152
	s_waitcnt lgkmcnt(1)
	v_mfma_f32_32x32x16_bf16 v[64:79], v[120:123], v[132:135], v[64:79]
	ds_read_b128 v[120:123], v215 offset:57344
	s_waitcnt lgkmcnt(1)
	v_mfma_f32_32x32x16_bf16 v[80:95], v[112:115], v[140:143], v[80:95]
	ds_read_b128 v[112:115], v216 offset:49152
	s_waitcnt lgkmcnt(1)
	v_mfma_f32_32x32x16_bf16 v[64:79], v[120:123], v[140:143], v[64:79]
	ds_read_b128 v[120:123], v216 offset:57344
	s_waitcnt lgkmcnt(1)
	v_mfma_f32_32x32x16_bf16 v[80:95], v[112:115], v[136:139], v[80:95]
	ds_read_b128 v[112:115], v217 offset:49152
	s_waitcnt lgkmcnt(1)
	v_mfma_f32_32x32x16_bf16 v[64:79], v[120:123], v[136:139], v[64:79]
	ds_read_b128 v[120:123], v217 offset:57344
	s_waitcnt lgkmcnt(1)
	v_mfma_f32_32x32x16_bf16 v[80:95], v[112:115], v[128:131], v[80:95]
	ds_read_b128 v[112:115], v218 offset:49152
	s_waitcnt lgkmcnt(1)
	v_mfma_f32_32x32x16_bf16 v[64:79], v[120:123], v[128:131], v[64:79]
	ds_read_b128 v[120:123], v218 offset:57344
	s_waitcnt lgkmcnt(1)
	v_mfma_f32_32x32x16_bf16 v[80:95], v[112:115], v[124:127], v[80:95]
	ds_read_b128 v[112:115], v219 offset:49152
	s_waitcnt lgkmcnt(1)
	v_mfma_f32_32x32x16_bf16 v[64:79], v[120:123], v[124:127], v[64:79]
	ds_read_b128 v[120:123], v219 offset:57344
	s_waitcnt lgkmcnt(1)
	v_mfma_f32_32x32x16_bf16 v[80:95], v[112:115], v[116:119], v[80:95]
	s_waitcnt lgkmcnt(0)
	v_mfma_f32_32x32x16_bf16 v[64:79], v[120:123], v[116:119], v[64:79]
	s_cbranch_scc1 .LBB0_595
	s_add_i32 s20, s38, s33
	s_add_i32 s20, s20, -5
	v_cmp_ge_i32_e32 vcc, s20, v223
	v_cmp_lt_i32_e64 s[16:17], s20, v224
	s_and_b64 s[38:39], vcc, s[16:17]
	v_mov_b32_e32 v127, 0xf149f2ca
	v_mov_b32_e32 v128, 0xf149f2ca
	v_mov_b32_e32 v125, 0xf149f2ca
	v_mov_b32_e32 v126, 0xf149f2ca
	v_mov_b32_e32 v123, 0xf149f2ca
	v_mov_b32_e32 v124, 0xf149f2ca
	v_mov_b32_e32 v120, 0xf149f2ca
	v_mov_b32_e32 v121, 0xf149f2ca
	v_mov_b32_e32 v118, 0xf149f2ca
	v_mov_b32_e32 v119, 0xf149f2ca
	v_mov_b32_e32 v116, 0xf149f2ca
	v_mov_b32_e32 v117, 0xf149f2ca
	v_mov_b32_e32 v114, 0xf149f2ca
	v_mov_b32_e32 v115, 0xf149f2ca
	v_mov_b32_e32 v112, 0xf149f2ca
	v_mov_b32_e32 v113, 0xf149f2ca
	v_mov_b32_e32 v143, 0xf149f2ca
	v_mov_b32_e32 v144, 0xf149f2ca
	v_mov_b32_e32 v141, 0xf149f2ca
	v_mov_b32_e32 v142, 0xf149f2ca
	v_mov_b32_e32 v139, 0xf149f2ca
	v_mov_b32_e32 v140, 0xf149f2ca
	v_mov_b32_e32 v137, 0xf149f2ca
	v_mov_b32_e32 v138, 0xf149f2ca
	v_mov_b32_e32 v135, 0xf149f2ca
	v_mov_b32_e32 v136, 0xf149f2ca
	v_mov_b32_e32 v133, 0xf149f2ca
	v_mov_b32_e32 v134, 0xf149f2ca
	v_mov_b32_e32 v131, 0xf149f2ca
	v_mov_b32_e32 v132, 0xf149f2ca
	v_mov_b32_e32 v129, 0xf149f2ca
	v_mov_b32_e32 v130, 0xf149f2ca
	s_and_saveexec_b64 s[16:17], s[38:39]
	s_cbranch_execz .LBB0_594
	v_sub_u32_e32 v112, v221, v220
	v_sub_u32_e32 v113, s20, v222
	s_movk_i32 s1, 0x7c
	v_mul_lo_u32 v113, v113, s1
	v_lshlrev_b32_e32 v112, 2, v112
	v_readlane_b32 s1, v254, 35
	s_nop 1
	v_add3_u32 v122, s1, v113, v112
	v_mov_b32_e32 v112, 0xf149f2ca
	v_mov_b32_e32 v113, 0xf149f2ca
	s_and_saveexec_b64 vcc, s[96:97]
	s_cbranch_execz .LBB0_531
	ds_read_b32 v113, v122 offset:60
	s_waitcnt lgkmcnt(0)
	v_add_f32_e32 v113, v80, v113

.LBB0_605:
	ds_read_b128 v[64:67], v212 offset:49152
	ds_read_b128 v[68:71], v212 offset:57344
	ds_read_b128 v[198:201], v213 offset:49152
	ds_read_b128 v[222:225], v213 offset:57344
	v_exp_f32_e32 v174, v174
	v_exp_f32_e32 v175, v175
	s_waitcnt lgkmcnt(3)
	v_mfma_f32_32x32x16_bf16 v[80:95], v[64:67], v[124:127], 0
	v_exp_f32_e32 v172, v172
	v_exp_f32_e32 v173, v173
	v_exp_f32_e32 v170, v170
	v_exp_f32_e32 v171, v171
	v_exp_f32_e32 v180, v168
	v_exp_f32_e32 v181, v169
	v_pk_add_f32 v[194:195], v[158:159], v[174:175]
	s_waitcnt lgkmcnt(2)
	v_mfma_f32_32x32x16_bf16 v[64:79], v[68:71], v[124:127], 0
	v_add_f32_e64 v228, v154, v170
	v_add_f32_e64 v229, v155, v171
	s_waitcnt lgkmcnt(1)
	v_mfma_f32_32x32x16_bf16 v[80:95], v[198:201], v[120:123], v[80:95]
	ds_read_b128 v[198:201], v214 offset:49152
	s_waitcnt lgkmcnt(1)
	v_mfma_f32_32x32x16_bf16 v[64:79], v[222:225], v[120:123], v[64:79]
	ds_read_b128 v[222:225], v214 offset:57344
	s_waitcnt lgkmcnt(1)
	v_mfma_f32_32x32x16_bf16 v[80:95], v[198:201], v[116:119], v[80:95]
	ds_read_b128 v[198:201], v215 offset:49152
	s_waitcnt lgkmcnt(1)
	v_mfma_f32_32x32x16_bf16 v[64:79], v[222:225], v[116:119], v[64:79]
	ds_read_b128 v[222:225], v215 offset:57344
	s_waitcnt lgkmcnt(1)
	v_mfma_f32_32x32x16_bf16 v[80:95], v[198:201], v[112:115], v[80:95]
	ds_read_b128 v[198:201], v216 offset:49152
	s_waitcnt lgkmcnt(1)
	v_mfma_f32_32x32x16_bf16 v[64:79], v[222:225], v[112:115], v[64:79]
	ds_read_b128 v[222:225], v216 offset:57344
	s_waitcnt lgkmcnt(1)
	v_mfma_f32_32x32x16_bf16 v[80:95], v[198:201], v[108:111], v[80:95]
	ds_read_b128 v[198:201], v217 offset:49152
	s_waitcnt lgkmcnt(1)
	v_mfma_f32_32x32x16_bf16 v[64:79], v[222:225], v[108:111], v[64:79]
	ds_read_b128 v[222:225], v217 offset:57344
	s_waitcnt lgkmcnt(1)
	v_mfma_f32_32x32x16_bf16 v[80:95], v[198:201], v[104:107], v[80:95]
	ds_read_b128 v[198:201], v218 offset:49152
	s_waitcnt lgkmcnt(1)
	v_mfma_f32_32x32x16_bf16 v[64:79], v[222:225], v[104:107], v[64:79]
	ds_read_b128 v[222:225], v218 offset:57344
	s_waitcnt lgkmcnt(1)
	v_mfma_f32_32x32x16_bf16 v[80:95], v[198:201], v[100:103], v[80:95]
	ds_read_b128 v[198:201], v219 offset:49152
	s_waitcnt lgkmcnt(1)
	v_mfma_f32_32x32x16_bf16 v[64:79], v[222:225], v[100:103], v[64:79]
	ds_read_b128 v[222:225], v219 offset:57344
	s_waitcnt lgkmcnt(1)
	v_mfma_f32_32x32x16_bf16 v[80:95], v[198:201], v[96:99], v[80:95]
	v_exp_f32_e32 v198, v166
	v_exp_f32_e32 v199, v167
	v_exp_f32_e32 v200, v164
	v_exp_f32_e32 v201, v165
	v_pk_add_f32 v[166:167], v[152:153], v[180:181]
	v_pk_add_f32 v[168:169], v[150:151], v[198:199]
	s_waitcnt lgkmcnt(0)
	v_mfma_f32_32x32x16_bf16 v[64:79], v[222:225], v[96:99], v[64:79]
	v_exp_f32_e32 v222, v162
	v_exp_f32_e32 v223, v163
	v_exp_f32_e32 v224, v160
	v_exp_f32_e32 v225, v161
	v_pk_add_f32 v[160:161], v[148:149], v[200:201]
	v_pk_add_f32 v[162:163], v[156:157], v[172:173]
	v_pk_add_f32 v[226:227], v[146:147], v[222:223]
	v_pk_add_f32 v[164:165], v[144:145], v[224:225]
	v_pk_add_f32 v[226:227], v[228:229], v[226:227]
	v_pk_add_f32 v[168:169], v[194:195], v[168:169]
	v_pk_add_f32 v[164:165], v[166:167], v[164:165]
	v_pk_add_f32 v[160:161], v[162:163], v[160:161]
	v_pk_add_f32 v[162:163], v[168:169], v[226:227]
	v_pk_add_f32 v[160:161], v[160:161], v[164:165]
	s_nop 0
	v_pk_add_f32 v[160:161], v[162:163], v[160:161]
	s_nop 0
	v_pk_add_f32 v[194:195], v[160:161], v[160:161] op_sel:[0,1] op_sel_hi:[1,0]
	v_cvt_pk_bf16_f32 v160, v158, v159
	v_cvt_pk_bf16_f32 v161, v156, v157
	v_cvt_pk_bf16_f32 v162, v154, v155
	v_cvt_pk_bf16_f32 v163, v152, v153
	v_cvt_pk_bf16_f32 v164, v150, v151
	s_nop 0
	v_mov_b32_e32 v195, v194
	s_nop 1
	v_permlane32_swap_b32_e32 v194, v195
	v_permlane32_swap_b32_e32 v160, v162
	v_cvt_pk_bf16_f32 v165, v148, v149
	v_cvt_pk_bf16_f32 v166, v146, v147
	v_cvt_pk_bf16_f32 v167, v144, v145
	v_cvt_pk_bf16_f32 v168, v174, v175
	v_cvt_pk_bf16_f32 v169, v172, v173
	v_cvt_pk_bf16_f32 v170, v170, v171
	v_cvt_pk_bf16_f32 v171, v180, v181
	v_cvt_pk_bf16_f32 v172, v198, v199
	v_cvt_pk_bf16_f32 v173, v200, v201
	v_cvt_pk_bf16_f32 v174, v222, v223
	v_cvt_pk_bf16_f32 v175, v224, v225
	v_permlane32_swap_b32_e32 v161, v163
	v_permlane32_swap_b32_e32 v164, v166
	v_permlane32_swap_b32_e32 v165, v167
	v_permlane32_swap_b32_e32 v168, v170
	v_permlane32_swap_b32_e32 v169, v171
	v_permlane32_swap_b32_e32 v172, v174
	v_permlane32_swap_b32_e32 v173, v175
	s_add_i32 s16, s12, -1
	s_and_b32 s1, s16, 0x3fffffc
	s_add_i32 s10, s15, 0xffffff80
	s_add_i32 s11, s15, 0xfffffd80
	s_cmp_eq_u32 s1, 0
	s_cselect_b64 vcc, -1, 0
	s_and_b64 s[8:9], vcc, exec
	s_cselect_b32 s1, s10, s11
	s_cselect_b32 s8, s28, s0
	s_cselect_b32 s10, s4, s30
	s_mul_hi_u32 s11, s1, s8
	s_mul_i32 s1, s1, s8
	s_cselect_b32 s9, s5, s31
	s_cselect_b32 s17, s2, s24
	s_cselect_b32 s18, s3, s25
	s_add_u32 s8, s10, s1
	s_addc_u32 s9, s9, s11
	s_add_u32 s10, s17, s1
	v_cndmask_b32_e32 v176, v192, v188, vcc
	v_cndmask_b32_e32 v152, v190, v186, vcc
	v_mov_b32_e32 v153, v177
	s_addc_u32 s11, s18, s11
	v_lshl_add_u64 v[144:145], s[10:11], 0, v[152:153]
	v_lshl_add_u64 v[148:149], s[10:11], 0, v[176:177]
	v_lshl_add_u64 v[152:153], s[8:9], 0, v[152:153]
	v_lshl_add_u64 v[156:157], s[8:9], 0, v[176:177]
	global_load_dwordx4 v[144:147], v[144:145], off
	s_nop 0
	global_load_dwordx4 v[148:151], v[148:149], off
	s_nop 0
	global_load_dwordx4 v[152:155], v[152:153], off
	s_nop 0
	global_load_dwordx4 v[156:159], v[156:157], off
	ds_read_b64_tr_b16 v[198:199], v185 offset:0
	ds_read_b64_tr_b16 v[200:201], v185 offset:0x800
	ds_read_b64_tr_b16 v[222:223], v185 offset:0x1000
	ds_read_b64_tr_b16 v[224:225], v185 offset:0x1800
	ds_read_b64_tr_b16 v[226:227], v185 offset:0x2000
	ds_read_b64_tr_b16 v[228:229], v185 offset:0x2800
	ds_read_b64_tr_b16 v[230:231], v185 offset:0x3000
	ds_read_b64_tr_b16 v[232:233], v185 offset:0x3800
	s_waitcnt lgkmcnt(0)
	s_nop 0
	v_mfma_f32_32x32x16_bf16 v[0:15], v[160:163], v[198:201], v[0:15]
	ds_read_b64_tr_b16 v[198:199], v185 offset:0x200
	ds_read_b64_tr_b16 v[200:201], v185 offset:0xa00
	v_mfma_f32_32x32x16_bf16 v[0:15], v[164:167], v[222:225], v[0:15]
	ds_read_b64_tr_b16 v[222:223], v185 offset:0x1200
	ds_read_b64_tr_b16 v[224:225], v185 offset:0x1a00
	v_mfma_f32_32x32x16_bf16 v[0:15], v[168:171], v[226:229], v[0:15]
	ds_read_b64_tr_b16 v[226:227], v185 offset:0x2200
	ds_read_b64_tr_b16 v[228:229], v185 offset:0x2a00
	v_mfma_f32_32x32x16_bf16 v[0:15], v[172:175], v[230:233], v[0:15]
	ds_read_b64_tr_b16 v[230:231], v185 offset:0x3200
	ds_read_b64_tr_b16 v[232:233], v185 offset:0x3a00
	s_waitcnt lgkmcnt(0)
	v_mfma_f32_32x32x16_bf16 v[48:63], v[160:163], v[198:201], v[48:63]
	ds_read_b64_tr_b16 v[198:199], v185 offset:0x400
	ds_read_b64_tr_b16 v[200:201], v185 offset:0xc00
	v_mfma_f32_32x32x16_bf16 v[48:63], v[164:167], v[222:225], v[48:63]
	ds_read_b64_tr_b16 v[222:223], v185 offset:0x1400
	ds_read_b64_tr_b16 v[224:225], v185 offset:0x1c00
	v_mfma_f32_32x32x16_bf16 v[48:63], v[168:171], v[226:229], v[48:63]
	ds_read_b64_tr_b16 v[226:227], v185 offset:0x2400
	ds_read_b64_tr_b16 v[228:229], v185 offset:0x2c00
	v_mfma_f32_32x32x16_bf16 v[48:63], v[172:175], v[230:233], v[48:63]
	ds_read_b64_tr_b16 v[230:231], v185 offset:0x3400
	ds_read_b64_tr_b16 v[232:233], v185 offset:0x3c00
	s_waitcnt lgkmcnt(0)
	v_mfma_f32_32x32x16_bf16 v[32:47], v[160:163], v[198:201], v[32:47]
	ds_read_b64_tr_b16 v[198:199], v185 offset:0x600
	ds_read_b64_tr_b16 v[200:201], v185 offset:0xe00
	v_mfma_f32_32x32x16_bf16 v[32:47], v[164:167], v[222:225], v[32:47]
	ds_read_b64_tr_b16 v[222:223], v185 offset:0x1600
	ds_read_b64_tr_b16 v[224:225], v185 offset:0x1e00
	v_mfma_f32_32x32x16_bf16 v[32:47], v[168:171], v[226:229], v[32:47]
	ds_read_b64_tr_b16 v[226:227], v185 offset:0x2600
	ds_read_b64_tr_b16 v[228:229], v185 offset:0x2e00
	v_mfma_f32_32x32x16_bf16 v[32:47], v[172:175], v[230:233], v[32:47]
	ds_read_b64_tr_b16 v[230:231], v185 offset:0x3600
	ds_read_b64_tr_b16 v[232:233], v185 offset:0x3e00
	s_waitcnt lgkmcnt(0)
	v_mfma_f32_32x32x16_bf16 v[16:31], v[160:163], v[198:201], v[16:31]
	v_max_f32_e32 v160, v81, v81
	v_max_f32_e32 v161, v80, v80
	v_max_f32_e32 v160, v161, v160
	v_max3_f32 v160, v160, v82, v83
	v_max3_f32 v160, v160, v84, v85
	v_max3_f32 v160, v160, v86, v87
	v_max3_f32 v160, v160, v88, v89
	v_max3_f32 v160, v160, v90, v91
	v_max3_f32 v160, v160, v92, v93
	v_mfma_f32_32x32x16_bf16 v[16:31], v[164:167], v[222:225], v[16:31]
	v_max3_f32 v160, v160, v94, v95
	v_max3_f32 v160, v160, v64, v65
	v_max3_f32 v160, v160, v66, v67
	v_max3_f32 v160, v160, v68, v69
	v_max3_f32 v160, v160, v70, v71
	v_max3_f32 v160, v160, v72, v73
	v_max3_f32 v160, v160, v74, v75
	v_max3_f32 v160, v160, v76, v77
	v_mfma_f32_32x32x16_bf16 v[16:31], v[168:171], v[226:229], v[16:31]
	v_max3_f32 v160, v160, v78, v79
	v_mov_b32_e32 v161, v160
	s_nop 1
	v_permlane32_swap_b32_e32 v160, v161
	v_max_f32_e32 v161, v161, v161
	v_max_f32_e32 v160, v160, v160
	v_max_f32_e32 v160, v160, v161
	v_sub_f32_e32 v161, v160, v197
	v_cmp_ge_f32_e32 vcc, s29, v161
	v_max_f32_e32 v161, v197, v197
	v_max_f32_e32 v160, v161, v160
	v_mfma_f32_32x32x16_bf16 v[16:31], v[172:175], v[230:233], v[16:31]
	v_sub_f32_e32 v161, v197, v160
	v_mul_f32_e32 v161, 0x3e0293ee, v161
	v_exp_f32_e32 v161, v161
	s_cmp_eq_u64 vcc, exec
	s_cselect_b64 s[8:9], -1, 0
	s_barrier
	s_waitcnt vmcnt(4)
	v_cndmask_b32_e64 v221, v161, 1.0, s[8:9]
	v_cmp_gt_f32_e32 vcc, 1.0, v221
	s_waitcnt vmcnt(7)
	ds_write_b128 v208, v[128:131]
	s_waitcnt vmcnt(6)
	ds_write_b128 v209, v[132:135]
	s_waitcnt vmcnt(5)
	ds_write_b128 v210, v[136:139] offset:32768
	s_waitcnt vmcnt(4)
	ds_write_b128 v211, v[140:143] offset:32768
	s_cbranch_vccz .LBB0_609
	s_and_saveexec_b64 s[10:11], s[6:7]
	ds_write_b32 v191, v221 offset:128
	s_or_b64 exec, exec, s[10:11]
	s_waitcnt lgkmcnt(0)
	v_add_u32_e32 v161, v183, v184
	ds_read_b128 v[162:165], v161 offset:224
	ds_read_b128 v[166:169], v161 offset:192
	ds_read_b128 v[170:173], v161 offset:160
	ds_read_b128 v[198:201], v161 offset:128
	s_waitcnt lgkmcnt(3)
	v_pk_mul_f32 v[12:13], v[12:13], v[162:163]
	s_waitcnt lgkmcnt(2)
	v_pk_mul_f32 v[8:9], v[8:9], v[166:167]
	s_waitcnt lgkmcnt(1)
	v_pk_mul_f32 v[4:5], v[4:5], v[170:171]
	v_pk_mul_f32 v[14:15], v[14:15], v[164:165]
	v_pk_mul_f32 v[10:11], v[10:11], v[168:169]
	v_pk_mul_f32 v[6:7], v[6:7], v[172:173]
	s_waitcnt lgkmcnt(0)
	v_pk_mul_f32 v[2:3], v[2:3], v[200:201]
	v_pk_mul_f32 v[0:1], v[0:1], v[198:199]
	v_pk_mul_f32 v[60:61], v[60:61], v[162:163]
	v_pk_mul_f32 v[56:57], v[56:57], v[166:167]
	v_pk_mul_f32 v[52:53], v[52:53], v[170:171]
	v_pk_mul_f32 v[62:63], v[62:63], v[164:165]
	v_pk_mul_f32 v[58:59], v[58:59], v[168:169]
	v_pk_mul_f32 v[54:55], v[54:55], v[172:173]
	v_pk_mul_f32 v[50:51], v[50:51], v[200:201]
	v_pk_mul_f32 v[48:49], v[48:49], v[198:199]
	v_pk_mul_f32 v[44:45], v[44:45], v[162:163]
	v_pk_mul_f32 v[40:41], v[40:41], v[166:167]
	v_pk_mul_f32 v[36:37], v[36:37], v[170:171]
	v_pk_mul_f32 v[46:47], v[46:47], v[164:165]
	v_pk_mul_f32 v[42:43], v[42:43], v[168:169]
	v_pk_mul_f32 v[38:39], v[38:39], v[172:173]
	v_pk_mul_f32 v[34:35], v[34:35], v[200:201]
	v_pk_mul_f32 v[32:33], v[32:33], v[198:199]
	v_pk_mul_f32 v[28:29], v[28:29], v[162:163]
	v_pk_mul_f32 v[24:25], v[24:25], v[166:167]
	v_pk_mul_f32 v[20:21], v[20:21], v[170:171]
	v_pk_mul_f32 v[30:31], v[30:31], v[164:165]
	v_pk_mul_f32 v[26:27], v[26:27], v[168:169]
	v_pk_mul_f32 v[22:23], v[22:23], v[172:173]
	v_pk_mul_f32 v[18:19], v[18:19], v[200:201]
	v_pk_mul_f32 v[16:17], v[16:17], v[198:199]
.LBB0_609:
	v_cndmask_b32_e64 v222, v160, v197, s[8:9]
	v_mul_f32_e32 v196, 0xbe0293ee, v222
	v_mov_b32_e32 v197, v196
	v_pk_fma_f32 v[94:95], v[94:95], s[36:37], v[196:197] op_sel_hi:[1,0,0]
	v_pk_fma_f32 v[92:93], v[92:93], s[36:37], v[196:197] op_sel_hi:[1,0,0]
	v_pk_fma_f32 v[90:91], v[90:91], s[36:37], v[196:197] op_sel_hi:[1,0,0]
	v_pk_fma_f32 v[88:89], v[88:89], s[36:37], v[196:197] op_sel_hi:[1,0,0]
	v_pk_fma_f32 v[86:87], v[86:87], s[36:37], v[196:197] op_sel_hi:[1,0,0]
	v_pk_fma_f32 v[84:85], v[84:85], s[36:37], v[196:197] op_sel_hi:[1,0,0]
	v_pk_fma_f32 v[82:83], v[82:83], s[36:37], v[196:197] op_sel_hi:[1,0,0]
	v_pk_fma_f32 v[80:81], v[80:81], s[36:37], v[196:197] op_sel_hi:[1,0,0]
	v_exp_f32_e32 v174, v82
	v_exp_f32_e32 v160, v80
	v_exp_f32_e32 v161, v81
	v_exp_f32_e32 v175, v83
	v_exp_f32_e32 v162, v84
	v_exp_f32_e32 v163, v85
	v_exp_f32_e32 v172, v86
	v_exp_f32_e32 v173, v87
	v_exp_f32_e32 v164, v88
	v_exp_f32_e32 v165, v89
	v_exp_f32_e32 v170, v90
	v_exp_f32_e32 v171, v91
	v_exp_f32_e32 v166, v92
	v_exp_f32_e32 v167, v93
	v_exp_f32_e32 v168, v94
	v_exp_f32_e32 v169, v95
	v_mov_b32_e32 v80, v196
	v_mov_b32_e32 v81, v196
	v_pk_fma_f32 v[180:181], v[78:79], s[36:37], v[80:81] op_sel_hi:[1,0,1]
	v_pk_fma_f32 v[200:201], v[76:77], s[36:37], v[80:81] op_sel_hi:[1,0,1]
	v_pk_fma_f32 v[228:229], v[74:75], s[36:37], v[80:81] op_sel_hi:[1,0,1]
	v_pk_fma_f32 v[230:231], v[72:73], s[36:37], v[80:81] op_sel_hi:[1,0,1]
	v_pk_fma_f32 v[232:233], v[70:71], s[36:37], v[80:81] op_sel_hi:[1,0,1]
	v_pk_fma_f32 v[234:235], v[68:69], s[36:37], v[80:81] op_sel_hi:[1,0,1]
	v_pk_fma_f32 v[236:237], v[66:67], s[36:37], v[80:81] op_sel_hi:[1,0,1]
	v_pk_fma_f32 v[238:239], v[64:65], s[36:37], v[196:197] op_sel_hi:[1,0,1]
	s_waitcnt lgkmcnt(0)
	s_barrier
	ds_read_b128 v[64:67], v212 offset:32768
	ds_read_b128 v[68:71], v212 offset:40960
	ds_read_b128 v[196:199], v213 offset:32768
	ds_read_b128 v[224:227], v213 offset:40960
	v_exp_f32_e32 v232, v232
	v_exp_f32_e32 v233, v233
	s_waitcnt lgkmcnt(3)
	v_mfma_f32_32x32x16_bf16 v[80:95], v[64:67], v[124:127], 0
	v_exp_f32_e32 v230, v230
	v_exp_f32_e32 v231, v231
	v_exp_f32_e32 v228, v228
	v_exp_f32_e32 v229, v229
	v_exp_f32_e32 v200, v200
	v_exp_f32_e32 v201, v201
	v_exp_f32_e32 v180, v180
	s_waitcnt lgkmcnt(2)
	v_mfma_f32_32x32x16_bf16 v[64:79], v[68:71], v[124:127], 0
	v_exp_f32_e32 v181, v181
	v_pk_add_f32 v[240:241], v[172:173], v[232:233]
	v_pk_add_f32 v[242:243], v[166:167], v[200:201]
	s_waitcnt lgkmcnt(1)
	v_mfma_f32_32x32x16_bf16 v[80:95], v[196:199], v[120:123], v[80:95]
	ds_read_b128 v[196:199], v214 offset:32768
	s_waitcnt lgkmcnt(1)
	v_mfma_f32_32x32x16_bf16 v[64:79], v[224:227], v[120:123], v[64:79]
	ds_read_b128 v[224:227], v214 offset:40960
	s_waitcnt lgkmcnt(1)
	v_mfma_f32_32x32x16_bf16 v[80:95], v[196:199], v[116:119], v[80:95]
	ds_read_b128 v[196:199], v215 offset:32768
	s_waitcnt lgkmcnt(1)
	v_mfma_f32_32x32x16_bf16 v[64:79], v[224:227], v[116:119], v[64:79]
	ds_read_b128 v[224:227], v215 offset:40960
	s_waitcnt lgkmcnt(1)
	v_mfma_f32_32x32x16_bf16 v[80:95], v[196:199], v[112:115], v[80:95]
	ds_read_b128 v[196:199], v216 offset:32768
	s_waitcnt lgkmcnt(1)
	v_mfma_f32_32x32x16_bf16 v[64:79], v[224:227], v[112:115], v[64:79]
	ds_read_b128 v[224:227], v216 offset:40960
	s_waitcnt lgkmcnt(1)
	v_mfma_f32_32x32x16_bf16 v[80:95], v[196:199], v[108:111], v[80:95]
	ds_read_b128 v[196:199], v217 offset:32768
	s_waitcnt lgkmcnt(1)
	v_mfma_f32_32x32x16_bf16 v[64:79], v[224:227], v[108:111], v[64:79]
	ds_read_b128 v[224:227], v217 offset:40960
	s_waitcnt lgkmcnt(1)
	v_mfma_f32_32x32x16_bf16 v[80:95], v[196:199], v[104:107], v[80:95]
	ds_read_b128 v[196:199], v218 offset:32768
	s_waitcnt lgkmcnt(1)
	v_mfma_f32_32x32x16_bf16 v[64:79], v[224:227], v[104:107], v[64:79]
	ds_read_b128 v[224:227], v218 offset:40960
	s_waitcnt lgkmcnt(1)
	v_mfma_f32_32x32x16_bf16 v[80:95], v[196:199], v[100:103], v[80:95]
	ds_read_b128 v[196:199], v219 offset:32768
	s_waitcnt lgkmcnt(1)
	v_mfma_f32_32x32x16_bf16 v[64:79], v[224:227], v[100:103], v[64:79]
	ds_read_b128 v[224:227], v219 offset:40960
	s_waitcnt lgkmcnt(1)
	v_mfma_f32_32x32x16_bf16 v[80:95], v[196:199], v[96:99], v[80:95]
	v_exp_f32_e32 v198, v238
	v_exp_f32_e32 v199, v239
	v_pk_add_f32 v[196:197], v[164:165], v[230:231]
	v_pk_add_f32 v[238:239], v[168:169], v[180:181]
	v_pk_add_f32 v[246:247], v[160:161], v[198:199]
	v_pk_add_f32 v[238:239], v[240:241], v[238:239]
	s_waitcnt lgkmcnt(0)
	v_mfma_f32_32x32x16_bf16 v[64:79], v[224:227], v[96:99], v[64:79]
	v_exp_f32_e32 v224, v236
	v_exp_f32_e32 v225, v237
	v_exp_f32_e32 v226, v234
	v_exp_f32_e32 v227, v235
	v_pk_add_f32 v[234:235], v[170:171], v[228:229]
	v_pk_add_f32 v[236:237], v[174:175], v[224:225]
	v_pk_add_f32 v[196:197], v[246:247], v[196:197]
	v_pk_add_f32 v[244:245], v[162:163], v[226:227]
	v_pk_add_f32 v[234:235], v[236:237], v[234:235]
	v_pk_add_f32 v[242:243], v[244:245], v[242:243]
	v_pk_add_f32 v[234:235], v[234:235], v[238:239]
	v_pk_add_f32 v[196:197], v[196:197], v[242:243]
	v_cvt_pk_bf16_f32 v160, v160, v161
	v_cvt_pk_bf16_f32 v161, v174, v175
	v_cvt_pk_bf16_f32 v162, v162, v163
	v_cvt_pk_bf16_f32 v163, v172, v173
	v_cvt_pk_bf16_f32 v164, v164, v165
	s_nop 0
	v_pk_add_f32 v[196:197], v[196:197], v[234:235]
	v_cvt_pk_bf16_f32 v165, v170, v171
	v_cvt_pk_bf16_f32 v166, v166, v167
	v_cvt_pk_bf16_f32 v167, v168, v169
	v_cvt_pk_bf16_f32 v168, v198, v199
	v_cvt_pk_bf16_f32 v169, v224, v225
	s_nop 0
	v_pk_add_f32 v[196:197], v[196:197], v[196:197] op_sel:[0,1] op_sel_hi:[1,0]
	v_cvt_pk_bf16_f32 v170, v226, v227
	v_cvt_pk_bf16_f32 v171, v232, v233
	v_cvt_pk_bf16_f32 v172, v230, v231
	v_cvt_pk_bf16_f32 v173, v228, v229
	v_cvt_pk_bf16_f32 v174, v200, v201
	s_nop 0
	v_mov_b32_e32 v223, v196
	v_cvt_pk_bf16_f32 v175, v180, v181
	s_nop 1
	v_permlane32_swap_b32_e32 v196, v223
	v_permlane32_swap_b32_e32 v160, v162
	v_permlane32_swap_b32_e32 v161, v163
	v_permlane32_swap_b32_e32 v164, v166
	v_permlane32_swap_b32_e32 v165, v167
	v_permlane32_swap_b32_e32 v168, v170
	v_permlane32_swap_b32_e32 v169, v171
	v_permlane32_swap_b32_e32 v172, v174
	v_permlane32_swap_b32_e32 v173, v175
	s_cmp_ge_u32 s12, s13
	s_cbranch_scc1 .LBB0_611
	s_and_b32 s1, s12, 0x3fffffc
	s_add_i32 s10, s15, 0xfffffe00
	s_cmp_eq_u32 s1, 0
	s_cselect_b64 vcc, -1, 0
	s_and_b64 s[8:9], vcc, exec
	s_cselect_b32 s1, s15, s10
	s_cselect_b32 s8, s28, s0
	s_cselect_b32 s10, s4, s30
	s_mul_hi_u32 s11, s1, s8
	s_mul_i32 s1, s1, s8
	s_cselect_b32 s9, s5, s31
	s_cselect_b32 s17, s2, s24
	s_cselect_b32 s18, s3, s25
	s_add_u32 s8, s10, s1
	s_addc_u32 s9, s9, s11
	s_add_u32 s10, s17, s1
	v_cndmask_b32_e32 v176, v192, v188, vcc
	v_cndmask_b32_e32 v136, v190, v186, vcc
	v_mov_b32_e32 v137, v177
	s_addc_u32 s11, s18, s11
	v_lshl_add_u64 v[128:129], s[10:11], 0, v[136:137]
	v_lshl_add_u64 v[132:133], s[10:11], 0, v[176:177]
	v_lshl_add_u64 v[136:137], s[8:9], 0, v[136:137]
	v_lshl_add_u64 v[140:141], s[8:9], 0, v[176:177]
	global_load_dwordx4 v[128:131], v[128:129], off
	s_nop 0
	global_load_dwordx4 v[132:135], v[132:133], off
	s_nop 0
	global_load_dwordx4 v[136:139], v[136:137], off
	s_nop 0
	global_load_dwordx4 v[140:143], v[140:141], off
